# all 128 forget-bias cumsum units run in chunk 0's P2 queue (chunks 1-3 queue = LRU units only)
# speedup vs baseline: 1.0003x; 1.0003x over previous
; #define LAS __attribute__((address_space(3)))
; template <class T_> __device__ __forceinline__ T_* as_global(T_* p) { return (T_*)(GAS T_*)p; }
; #define KA() ({ KArgs p_ = (KArgs)__builtin_amdgcn_kernarg_segment_ptr(); asm volatile("" : "+s"(p_)); p_; })
; __global__ void __launch_bounds__(NWAVES * 64, 2) hybrid_fwd(Args args) {
;     ...
;         {
;             {
;                 KArgs ka = KA(); const LruPtrs lp{as_global(ka->conv_w), as_global(ka->conv_b), as_global(ka->b_lru_r), as_global(ka->b_lru_i), as_global(ka->ws)};
;                 unsigned* qc = (unsigned*)(wsl + WS_CTL) + CW_Q + (chunk * 2 + 0) * 64; LAS unsigned* slot = (LAS unsigned*)(lds + LDSCTL_OFF + 64);
;                 for (;;) {
;                     if (threadIdx.x == 0) *slot = __hip_atomic_fetch_add(qc, 1u, __ATOMIC_RELAXED, __HIP_MEMORY_SCOPE_AGENT);
;                     __syncthreads();
;                     const int L = __builtin_amdgcn_readfirstlane((int)*slot);
;                     __syncthreads();
;                     if (L >= CHB * 16 * 32 + CHB * 16) break;
;                     if (L >= CHB * 16) { const int L1 = L - CHB * 16; lru_unit<1>(lp, lds, chunk, L1 >> 9, (L1 >> 5) & 15, L1 & 31); }
;                     else cumsum_unit(CB + (size_t)(chunk * CHB * 16 + L) * T, lds);
.LBB0_402:
	s_or_b64 exec, exec, s[4:5]
	s_mov_b64 s[4:5], s[0:1]
	s_lshl_b32 s2, s95, 24
	s_waitcnt lgkmcnt(0)
	s_barrier
	s_add_u32 s77, s36, 0x3200000
	s_load_dwordx4 s[12:15], s[4:5], 0x20
	s_load_dwordx2 s[6:7], s[4:5], 0x38
	s_load_dwordx2 s[8:9], s[4:5], 0x48
	s_load_dwordx2 s[40:41], s[4:5], 0xa0
	s_addc_u32 s33, s37, 0
	s_lshl_b32 s18, s95, 7
	s_lshl_b64 s[4:5], s[18:19], 2
	v_writelane_b32 v255, s2, 8
	s_add_u32 s2, s36, s4
	s_addc_u32 s4, s37, s5
	s_add_u32 s38, s2, 0xc000
	s_addc_u32 s39, s4, 0
	s_lshl_b32 s25, s95, 5
	s_cmp_eq_u32 s95, 0
	s_cselect_b32 s100, 0x80, 0
	s_add_i32 s101, s100, 0x3ff
	s_mov_b32 s99, 1
	s_branch .LBB0_406

; __global__ void __launch_bounds__(NWAVES * 64, 2) hybrid_fwd(Args args) {
;     ...
;                 for (;;) {
;                     if (threadIdx.x == 0) *slot = __hip_atomic_fetch_add(qc, 1u, __ATOMIC_RELAXED, __HIP_MEMORY_SCOPE_AGENT);
;                     __syncthreads();
;                     const int L = __builtin_amdgcn_readfirstlane((int)*slot);
;                     __syncthreads();
;                     if (L >= CHB * 16 * 32 + CHB * 16) break;
;                     if (L >= CHB * 16) { const int L1 = L - CHB * 16; lru_unit<1>(lp, lds, chunk, L1 >> 9, (L1 >> 5) & 15, L1 & 31); }
;                     else cumsum_unit(CB + (size_t)(chunk * CHB * 16 + L) * T, lds);
.LBB0_410:
	s_or_b64 exec, exec, s[4:5]
	v_mov_b32_e32 v0, s86
	s_waitcnt lgkmcnt(0)
	s_barrier
	ds_read_b32 v0, v0
	s_mov_b64 s[4:5], -1
	s_waitcnt lgkmcnt(0)
	s_barrier
	v_readfirstlane_b32 s46, v0
	s_cmp_gt_i32 s46, s101
	s_cbranch_scc1 .LBB0_405
	s_mov_b32 s99, 0
	s_cmpk_lt_i32 s46, 0x480
	s_cbranch_scc0 .Lq2_nopf
	s_mov_b32 s99, 1
	s_and_saveexec_b64 s[42:43], s[10:11]
	s_cbranch_execz .Lq2_nopx
	v_mov_b32_e32 v252, v230
	global_atomic_add v252, v1, v252, s[38:39] sc0

; #define LAS __attribute__((address_space(3)))
; __device__ __forceinline__ void cumsum_unit(float* CBh, LAS unsigned char* lds) {
;     int tid_ = threadIdx.x; asm volatile("" : "+v"(tid_));
;     const int tid = tid_, lane = tid & 63, w = tid >> 6;
;     LAS float* wsum = (LAS float*)(lds + RING_OFF + 16384);
;     f32x4 v[4]; float s = 0.f;
; #pragma unroll
;     for (int j = 0; j < 4; ++j) { v[j] = *(const f32x4*)(CBh + tid * 16 + 4 * j);
; #pragma unroll
;         for (int e = 0; e < 4; ++e) { s += v[j][e]; v[j][e] = s; } }
;     float inc = s;
; #pragma unroll
;     for (int d = 1; d < 64; d <<= 1) { const float o = __builtin_bit_cast(float, __builtin_amdgcn_ds_bpermute((lane - d) << 2, __builtin_bit_cast(int, inc))); if (lane >= d) inc += o; }
;     if (lane == 63) wsum[w] = inc;
;     __syncthreads();
;     float off = inc - s;
;     for (int ww = 0; ww < w; ++ww) off += wsum[ww];
; __global__ void __launch_bounds__(NWAVES * 64, 2) hybrid_fwd(Args args) {
;     ...
;                     else cumsum_unit(CB + (size_t)(chunk * CHB * 16 + L) * T, lds);
.Lq2_nopf:
	s_cmp_lt_i32 s46, s100
	s_cbranch_scc0 .LBB0_419
	s_add_i32 s4, s46, s25
	s_ashr_i32 s5, s4, 31
	s_lshl_b64 s[4:5], s[4:5], 15
	v_mov_b32_e32 v28, v236
	s_add_u32 s4, s77, s4
	s_addc_u32 s5, s33, s5
	v_lshlrev_b32_e32 v2, 4, v28
	v_ashrrev_i32_e32 v3, 31, v2
	v_lshl_add_u64 v[2:3], v[2:3], 2, s[4:5]
	global_load_dwordx4 v[4:7], v[2:3], off
	global_load_dwordx4 v[8:11], v[2:3], off offset:16
	global_load_dwordx4 v[20:23], v[2:3], off offset:32
	global_load_dwordx4 v[24:27], v[2:3], off offset:48
	v_and_b32_e32 v0, 63, v28
	v_lshlrev_b32_e32 v29, 2, v0
	v_add_u32_e32 v30, -4, v29
	v_cmp_eq_u32_e32 vcc, 0, v0
	s_waitcnt vmcnt(3)
	v_add_f32_e32 v18, 0, v4
	v_add_f32_e32 v19, v5, v18
	v_add_f32_e32 v16, v6, v19
	v_add_f32_e32 v17, v7, v16
	s_waitcnt vmcnt(2)
	v_add_f32_e32 v14, v8, v17
	v_add_f32_e32 v15, v9, v14
	v_add_f32_e32 v12, v10, v15
	v_add_f32_e32 v13, v11, v12
	s_waitcnt vmcnt(1)
	v_add_f32_e32 v10, v20, v13
	v_add_f32_e32 v11, v21, v10
	v_add_f32_e32 v8, v22, v11
	v_add_f32_e32 v9, v23, v8
	s_waitcnt vmcnt(0)
	v_add_f32_e32 v6, v24, v9
	v_add_f32_e32 v7, v25, v6
	v_add_f32_e32 v4, v26, v7
	v_add_f32_e32 v5, v27, v4
	ds_bpermute_b32 v20, v30, v5
	v_add_u32_e32 v21, -8, v29
	v_add_u32_e32 v22, -16, v29
	s_waitcnt lgkmcnt(0)
	v_add_f32_e32 v20, v5, v20
	v_cndmask_b32_e32 v20, v20, v5, vcc
	ds_bpermute_b32 v21, v21, v20
	v_cmp_gt_u32_e32 vcc, 2, v0
	s_waitcnt lgkmcnt(0)
	v_add_f32_e32 v21, v20, v21
	v_cndmask_b32_e32 v20, v21, v20, vcc
	ds_bpermute_b32 v21, v22, v20
	v_cmp_gt_u32_e32 vcc, 4, v0
	v_subrev_u32_e32 v22, 32, v29
	s_waitcnt lgkmcnt(0)
	v_add_f32_e32 v21, v20, v21
	v_cndmask_b32_e32 v20, v21, v20, vcc
	ds_bpermute_b32 v21, v22, v20
	v_cmp_gt_u32_e32 vcc, 8, v0
	v_subrev_u32_e32 v22, 64, v29
	s_waitcnt lgkmcnt(0)
	v_add_f32_e32 v21, v20, v21
	v_cndmask_b32_e32 v20, v21, v20, vcc
	ds_bpermute_b32 v21, v22, v20
	v_cmp_gt_u32_e32 vcc, 16, v0
	v_add_u32_e32 v22, 0xffffff80, v29
	s_waitcnt lgkmcnt(0)
	v_add_f32_e32 v21, v20, v21
	v_cndmask_b32_e32 v21, v21, v20, vcc
	ds_bpermute_b32 v22, v22, v21
	v_ashrrev_i32_e32 v20, 6, v28
	v_cmp_eq_u32_e32 vcc, 63, v0
	s_waitcnt lgkmcnt(0)
	v_add_f32_e32 v22, v21, v22
	s_and_saveexec_b64 s[4:5], vcc
	v_lshl_add_u32 v23, v20, 2, 0
	ds_write_b32 v23, v22 offset:16384
	s_or_b64 exec, exec, s[4:5]
	v_cmp_gt_u32_e32 vcc, 32, v0
	s_waitcnt lgkmcnt(0)
	s_barrier
	v_cndmask_b32_e32 v0, v22, v21, vcc
	v_sub_f32_e32 v0, v0, v5
	v_cmp_lt_i32_e32 vcc, 0, v20
	s_and_saveexec_b64 s[4:5], vcc
	s_cbranch_execz .LBB0_418
	s_add_i32 s2, 0, 0x4000
	s_mov_b64 s[42:43], 0

; #define GAS __attribute__((address_space(1)))
; #define LAS __attribute__((address_space(3)))
; template <int PASS>
; __device__ __forceinline__ void lru_unit(const LruPtrs& args, LAS unsigned char* lds, int chunk, int bl, int g, int ck) {
;     ...
;     const int tl = ck * 256 + w * 32 + n;
;     const size_t zr = (size_t)bl * T + tl;
;     const int cb0 = g * 64 + 4 * hi;
;     float av[8][4], uv[8][4]; v4u gtile[4]; unsigned gagg[8];
;     if (PASS == 1) {
;         { const float* src = (w < 4) ? args.conv_w + w * D : (w == 4) ? args.conv_b : (w == 5) ? args.b_lru_r : (w == 6) ? args.b_lru_i : (const float*)(ws + WS_COEF);
;           PRM[w * 64 + lane] = ((const GAS float*)src)[g * 64 + lane]; }
;         LAS bf16* XT = (LAS bf16*)(lds + RING_OFF + 32768 + w * 4864);
;         {
;             const int tl0 = ck * 256 + w * 32;
;             v4u xv[5];
; #pragma unroll
;             for (int i = 0; i < 5; ++i) { const int idx = lane + 64 * i, r = idx >> 3, ch = idx & 7; const int ts = tl0 - 3 + r;
;                 xv[i] = (v4u){0u, 0u, 0u, 0u};
;                 if (r < 35 && ts >= 0) xv[i] = *(const GAS v4u*)(Z + ((size_t)bl * T + ts) * LDZ + ZC_AX + g * 64 + ch * 8); }
; __global__ void __launch_bounds__(NWAVES * 64, 2) hybrid_fwd(Args args) {
;     ...
;                     if (L >= CHB * 16 * 32 + CHB * 16) break;
;                     if (L >= CHB * 16) { const int L1 = L - CHB * 16; lru_unit<1>(lp, lds, chunk, L1 >> 9, (L1 >> 5) & 15, L1 & 31); }
.LBB0_433:
	s_sub_i32 s49, s46, s100
	s_bfe_u32 s2, s49, 0x40005
	v_and_b32_e32 v86, 63, v24
	s_lshl_b32 s44, s2, 6
	v_or_b32_e32 v0, s44, v86
	v_lshlrev_b32_e32 v0, 2, v0
	global_load_dword v178, v0, s[4:5]
	s_and_b32 s45, s46, 31
	s_lshl_b32 s51, s48, 5
	s_and_b32 s47, s18, 0xffffffc0
	s_lshl_b32 s52, s45, 8
	s_lshr_b32 s46, s49, 9
	s_lshl_b32 s53, s47, 2
	s_add_i32 s51, s52, s51
	v_lshlrev_b32_e32 v0, 3, v24
	s_lshl_b32 s50, s46, 13
	s_add_i32 s53, s53, 0
	s_lshl_b32 s52, s2, 7
	s_add_i32 s51, s51, -3
	v_and_b32_e32 v26, 56, v0
	s_add_u32 s52, s42, s52
	v_bfe_u32 v25, v24, 3, 3
	v_lshlrev_b32_e32 v0, 1, v26
	v_lshl_add_u32 v179, v86, 2, s53
	s_addc_u32 s53, s43, 0
	s_mov_b64 s[4:5], 0x13c00000
	v_add_u32_e32 v3, s51, v25
	v_lshl_add_u64 v[4:5], s[52:53], 0, v[0:1]
	v_mov_b32_e32 v2, 0
	v_mov_b32_e32 v6, 0
	v_mov_b32_e32 v7, 0
	v_mov_b32_e32 v8, 0
	v_cmp_lt_i32_e32 vcc, -1, v3
	v_lshl_add_u64 v[22:23], v[4:5], 0, s[4:5]
	v_mov_b32_e32 v9, 0
	s_and_saveexec_b64 s[4:5], vcc
	s_cbranch_execz .LBB0_435
	v_add_u32_e32 v0, s50, v3
	v_lshlrev_b64 v[4:5], 11, v[0:1]
	v_lshl_add_u64 v[4:5], v[22:23], 0, v[4:5]
	global_load_dwordx4 v[6:9], v[4:5], off
